# attention steady loop: next tile's K fragment LDS reads issued one P.V gap earlier (five gaps instead of four before the closing lgkmcnt(0) + barrier)
# speedup vs baseline: 1.0058x; 1.0004x over previous
.LBB0_311:
	v_exp_f32_e32 v128, v128
	v_exp_f32_e32 v129, v129
	v_exp_f32_e32 v130, v130
	ds_read_b64_tr_b16 v[108:109], v217 offset:34816
	ds_read_b64_tr_b16 v[110:111], v217 offset:35328
	v_mfma_f32_32x32x16_bf16 v[48:63], v[148:151], v[80:83], v[48:63]
	v_exp_f32_e32 v131, v131
	v_exp_f32_e32 v132, v132
	v_exp_f32_e32 v133, v133
	ds_read_b64_tr_b16 v[188:189], v217 offset:38912
	ds_read_b64_tr_b16 v[190:191], v217 offset:39424
	s_waitcnt lgkmcnt(12)
	v_mfma_f32_32x32x16_bf16 v[32:47], v[144:147], v[84:87], v[32:47]
	v_exp_f32_e32 v134, v134
	v_exp_f32_e32 v135, v135
	v_exp_f32_e32 v136, v136
	ds_read_b64_tr_b16 v[84:85], v217 offset:35840
	ds_read_b64_tr_b16 v[86:87], v217 offset:36352
	v_mfma_f32_32x32x16_bf16 v[48:63], v[144:147], v[88:91], v[48:63]
	v_exp_f32_e32 v137, v137
	v_exp_f32_e32 v138, v138
	v_exp_f32_e32 v139, v139
	ds_read_b64_tr_b16 v[88:89], v217 offset:39936
	ds_read_b64_tr_b16 v[90:91], v217 offset:40448
	v_add_u32_e32 v227, s22, v247
	ds_read_b128 v[80:83], v227
	ds_read_b128 v[200:203], v227 offset:512
	s_waitcnt lgkmcnt(14)
	v_mfma_f32_32x32x16_bf16 v[16:31], v[164:167], v[92:95], v[16:31]
	v_exp_f32_e32 v140, v140
	v_exp_f32_e32 v141, v141
	v_exp_f32_e32 v142, v142
	ds_read_b128 v[204:207], v227 offset:2048
	ds_read_b128 v[196:199], v227 offset:2560
	v_mfma_f32_32x32x16_bf16 v[0:15], v[164:167], v[96:99], v[0:15]
	v_exp_f32_e32 v143, v143
	v_exp_f32_e32 v112, v112
	v_exp_f32_e32 v113, v113
	ds_read_b128 v[192:195], v227 offset:4096
	ds_read_b128 v[184:187], v227 offset:4608
	s_waitcnt lgkmcnt(14)
	v_mfma_f32_32x32x16_bf16 v[16:31], v[156:159], v[100:103], v[16:31]
	v_exp_f32_e32 v114, v114
	v_exp_f32_e32 v115, v115
	v_exp_f32_e32 v116, v116
	ds_read_b128 v[180:183], v227 offset:6144
	ds_read_b128 v[176:179], v227 offset:6656
	v_mfma_f32_32x32x16_bf16 v[0:15], v[156:159], v[104:107], v[0:15]
	v_exp_f32_e32 v117, v117
	v_exp_f32_e32 v118, v118
	v_exp_f32_e32 v119, v119
	s_waitcnt lgkmcnt(12)
	v_mfma_f32_32x32x16_bf16 v[16:31], v[148:151], v[108:111], v[16:31]
	v_exp_f32_e32 v120, v120
	v_exp_f32_e32 v121, v121
	v_exp_f32_e32 v122, v122
	v_mfma_f32_32x32x16_bf16 v[0:15], v[148:151], v[188:191], v[0:15]
	v_exp_f32_e32 v123, v123
	v_exp_f32_e32 v124, v124
	v_exp_f32_e32 v125, v125
	s_waitcnt lgkmcnt(8)
	v_mfma_f32_32x32x16_bf16 v[16:31], v[144:147], v[84:87], v[16:31]
	v_exp_f32_e32 v126, v126
	v_exp_f32_e32 v127, v127
	v_mfma_f32_32x32x16_bf16 v[0:15], v[144:147], v[88:91], v[0:15]
	s_waitcnt vmcnt(3) lgkmcnt(0)
	s_barrier
	s_cmp_eq_u64 s[20:21], 0
	s_cbranch_scc0 .Lresc_a

.LBB0_314:
	v_exp_f32_e32 v96, v96
	v_exp_f32_e32 v97, v97
	v_exp_f32_e32 v98, v98
	ds_read_b64_tr_b16 v[140:141], v209 offset:34816
	ds_read_b64_tr_b16 v[142:143], v209 offset:35328
	v_mfma_f32_32x32x16_bf16 v[48:63], v[148:151], v[112:115], v[48:63]
	v_exp_f32_e32 v99, v99
	v_exp_f32_e32 v100, v100
	v_exp_f32_e32 v101, v101
	ds_read_b64_tr_b16 v[112:113], v209 offset:38912
	ds_read_b64_tr_b16 v[114:115], v209 offset:39424
	s_waitcnt lgkmcnt(12)
	v_mfma_f32_32x32x16_bf16 v[32:47], v[144:147], v[116:119], v[32:47]
	v_exp_f32_e32 v102, v102
	v_exp_f32_e32 v103, v103
	v_exp_f32_e32 v104, v104
	ds_read_b64_tr_b16 v[116:117], v209 offset:35840
	ds_read_b64_tr_b16 v[118:119], v209 offset:36352
	v_mfma_f32_32x32x16_bf16 v[48:63], v[144:147], v[120:123], v[48:63]
	v_exp_f32_e32 v105, v105
	v_exp_f32_e32 v106, v106
	v_exp_f32_e32 v107, v107
	ds_read_b64_tr_b16 v[120:121], v209 offset:39936
	ds_read_b64_tr_b16 v[122:123], v209 offset:40448
	v_add_u32_e32 v227, s66, v247
	ds_read_b128 v[204:207], v227
	ds_read_b128 v[200:203], v227 offset:512
	s_waitcnt lgkmcnt(14)
	v_mfma_f32_32x32x16_bf16 v[16:31], v[164:167], v[124:127], v[16:31]
	v_exp_f32_e32 v108, v108
	v_exp_f32_e32 v109, v109
	v_exp_f32_e32 v110, v110
	ds_read_b128 v[196:199], v227 offset:2048
	ds_read_b128 v[192:195], v227 offset:2560
	v_mfma_f32_32x32x16_bf16 v[0:15], v[164:167], v[128:131], v[0:15]
	v_exp_f32_e32 v111, v111
	v_exp_f32_e32 v80, v80
	v_exp_f32_e32 v81, v81
	ds_read_b128 v[188:191], v227 offset:4096
	ds_read_b128 v[184:187], v227 offset:4608
	s_waitcnt lgkmcnt(14)
	v_mfma_f32_32x32x16_bf16 v[16:31], v[156:159], v[132:135], v[16:31]
	v_exp_f32_e32 v82, v82
	v_exp_f32_e32 v83, v83
	v_exp_f32_e32 v84, v84
	ds_read_b128 v[180:183], v227 offset:6144
	ds_read_b128 v[176:179], v227 offset:6656
	v_mfma_f32_32x32x16_bf16 v[0:15], v[156:159], v[136:139], v[0:15]
	v_exp_f32_e32 v85, v85
	v_exp_f32_e32 v86, v86
	v_exp_f32_e32 v87, v87
	s_waitcnt lgkmcnt(12)
	v_mfma_f32_32x32x16_bf16 v[16:31], v[148:151], v[140:143], v[16:31]
	v_exp_f32_e32 v88, v88
	v_exp_f32_e32 v89, v89
	v_exp_f32_e32 v90, v90
	v_mfma_f32_32x32x16_bf16 v[0:15], v[148:151], v[112:115], v[0:15]
	v_exp_f32_e32 v91, v91
	v_exp_f32_e32 v92, v92
	v_exp_f32_e32 v93, v93
	s_waitcnt lgkmcnt(8)
	v_mfma_f32_32x32x16_bf16 v[16:31], v[144:147], v[116:119], v[16:31]
	v_exp_f32_e32 v94, v94
	v_exp_f32_e32 v95, v95
	v_mfma_f32_32x32x16_bf16 v[0:15], v[144:147], v[120:123], v[0:15]
	s_waitcnt vmcnt(3) lgkmcnt(0)
	s_barrier
	s_cmp_eq_u64 s[20:21], 0
	s_cbranch_scc0 .Lresc_b
